# non-temporal hint also on the gate / running-Y scratch loads of the merge epilogue (loads only)
# speedup vs baseline: 1.0148x; 1.0148x over previous
.Lmrg_seg0:
	s_mov_b64 s[70:71], s[72:73]
	v_mov_b32_e32 v230, 0
	v_mov_b32_e32 v231, 0
	s_add_u32 s4, s70, 0x0
	s_addc_u32 s5, s71, 0
	global_load_dwordx4 v[130:133], v232, s[4:5] nt
	s_add_u32 s4, s70, 0x2000
	s_addc_u32 s5, s71, 0
	global_load_dwordx4 v[134:137], v232, s[4:5] nt
	s_add_u32 s4, s70, 0x4000
	s_addc_u32 s5, s71, 0
	global_load_dwordx4 v[156:159], v232, s[4:5] nt
	s_add_u32 s4, s70, 0x6000
	s_addc_u32 s5, s71, 0
	global_load_dwordx4 v[162:165], v232, s[4:5] nt
	s_add_u32 s4, s70, 0x8000
	s_addc_u32 s5, s71, 0
	global_load_dwordx4 v[166:169], v232, s[4:5] nt
	s_add_u32 s4, s70, 0xa000
	s_addc_u32 s5, s71, 0
	global_load_dwordx4 v[170:173], v232, s[4:5] nt
	s_add_u32 s4, s70, 0xc000
	s_addc_u32 s5, s71, 0
	global_load_dwordx4 v[174:177], v232, s[4:5] nt
	s_add_u32 s4, s70, 0xe000
	s_addc_u32 s5, s71, 0
	global_load_dwordx4 v[178:181], v232, s[4:5] nt
	s_waitcnt vmcnt(7)
	v_lshlrev_b32_e32 v224, 16, v130
	v_and_b32_e32 v225, 0xffff0000, v130
	v_pk_fma_f32 v[126:127], v[126:127], v[224:225], v[230:231]
	v_lshlrev_b32_e32 v226, 16, v131
	v_and_b32_e32 v227, 0xffff0000, v131
	v_pk_fma_f32 v[128:129], v[128:129], v[226:227], v[230:231]
	v_lshlrev_b32_e32 v224, 16, v132
	v_and_b32_e32 v225, 0xffff0000, v132
	v_pk_fma_f32 v[122:123], v[122:123], v[224:225], v[230:231]
	v_lshlrev_b32_e32 v226, 16, v133
	v_and_b32_e32 v227, 0xffff0000, v133
	v_pk_fma_f32 v[124:125], v[124:125], v[226:227], v[230:231]
	v_cvt_pk_bf16_f32 v126, v126, v127
	v_cvt_pk_bf16_f32 v127, v128, v129
	v_cvt_pk_bf16_f32 v128, v122, v123
	v_cvt_pk_bf16_f32 v129, v124, v125
	s_add_u32 s76, s72, 0x0
	s_addc_u32 s77, s73, 0
	global_store_dwordx4 v232, v[126:129], s[76:77]
	s_add_u32 s4, s70, 0x10000
	s_addc_u32 s5, s71, 0
	global_load_dwordx4 v[130:133], v232, s[4:5] nt
	s_waitcnt vmcnt(8)
	v_lshlrev_b32_e32 v224, 16, v134
	v_and_b32_e32 v225, 0xffff0000, v134
	v_pk_fma_f32 v[118:119], v[118:119], v[224:225], v[230:231]
	v_lshlrev_b32_e32 v226, 16, v135
	v_and_b32_e32 v227, 0xffff0000, v135
	v_pk_fma_f32 v[120:121], v[120:121], v[226:227], v[230:231]
	v_lshlrev_b32_e32 v224, 16, v136
	v_and_b32_e32 v225, 0xffff0000, v136
	v_pk_fma_f32 v[114:115], v[114:115], v[224:225], v[230:231]
	v_lshlrev_b32_e32 v226, 16, v137
	v_and_b32_e32 v227, 0xffff0000, v137
	v_pk_fma_f32 v[116:117], v[116:117], v[226:227], v[230:231]
	v_cvt_pk_bf16_f32 v118, v118, v119
	v_cvt_pk_bf16_f32 v119, v120, v121
	v_cvt_pk_bf16_f32 v120, v114, v115
	v_cvt_pk_bf16_f32 v121, v116, v117
	s_add_u32 s76, s72, 0x2000
	s_addc_u32 s77, s73, 0
	global_store_dwordx4 v232, v[118:121], s[76:77]
	s_add_u32 s4, s70, 0x12000
	s_addc_u32 s5, s71, 0
	global_load_dwordx4 v[134:137], v232, s[4:5] nt
	s_waitcnt vmcnt(9)
	v_lshlrev_b32_e32 v224, 16, v156
	v_and_b32_e32 v225, 0xffff0000, v156
	v_pk_fma_f32 v[110:111], v[110:111], v[224:225], v[230:231]
	v_lshlrev_b32_e32 v226, 16, v157
	v_and_b32_e32 v227, 0xffff0000, v157
	v_pk_fma_f32 v[112:113], v[112:113], v[226:227], v[230:231]
	v_lshlrev_b32_e32 v224, 16, v158
	v_and_b32_e32 v225, 0xffff0000, v158
	v_pk_fma_f32 v[106:107], v[106:107], v[224:225], v[230:231]
	v_lshlrev_b32_e32 v226, 16, v159
	v_and_b32_e32 v227, 0xffff0000, v159
	v_pk_fma_f32 v[108:109], v[108:109], v[226:227], v[230:231]
	v_cvt_pk_bf16_f32 v110, v110, v111
	v_cvt_pk_bf16_f32 v111, v112, v113
	v_cvt_pk_bf16_f32 v112, v106, v107
	v_cvt_pk_bf16_f32 v113, v108, v109
	s_add_u32 s76, s72, 0x4000
	s_addc_u32 s77, s73, 0
	global_store_dwordx4 v232, v[110:113], s[76:77]
	s_add_u32 s4, s70, 0x14000
	s_addc_u32 s5, s71, 0
	global_load_dwordx4 v[156:159], v232, s[4:5] nt
	s_waitcnt vmcnt(10)
	v_lshlrev_b32_e32 v224, 16, v162
	v_and_b32_e32 v225, 0xffff0000, v162
	v_pk_fma_f32 v[102:103], v[102:103], v[224:225], v[230:231]
	v_lshlrev_b32_e32 v226, 16, v163
	v_and_b32_e32 v227, 0xffff0000, v163
	v_pk_fma_f32 v[104:105], v[104:105], v[226:227], v[230:231]
	v_lshlrev_b32_e32 v224, 16, v164
	v_and_b32_e32 v225, 0xffff0000, v164
	v_pk_fma_f32 v[98:99], v[98:99], v[224:225], v[230:231]
	v_lshlrev_b32_e32 v226, 16, v165
	v_and_b32_e32 v227, 0xffff0000, v165
	v_pk_fma_f32 v[100:101], v[100:101], v[226:227], v[230:231]
	v_cvt_pk_bf16_f32 v102, v102, v103
	v_cvt_pk_bf16_f32 v103, v104, v105
	v_cvt_pk_bf16_f32 v104, v98, v99
	v_cvt_pk_bf16_f32 v105, v100, v101
	s_add_u32 s76, s72, 0x6000
	s_addc_u32 s77, s73, 0
	global_store_dwordx4 v232, v[102:105], s[76:77]
	s_add_u32 s4, s70, 0x16000
	s_addc_u32 s5, s71, 0
	global_load_dwordx4 v[162:165], v232, s[4:5] nt
	s_waitcnt vmcnt(11)
	v_lshlrev_b32_e32 v224, 16, v166
	v_and_b32_e32 v225, 0xffff0000, v166
	v_pk_fma_f32 v[94:95], v[94:95], v[224:225], v[230:231]
	v_lshlrev_b32_e32 v226, 16, v167
	v_and_b32_e32 v227, 0xffff0000, v167
	v_pk_fma_f32 v[96:97], v[96:97], v[226:227], v[230:231]
	v_lshlrev_b32_e32 v224, 16, v168
	v_and_b32_e32 v225, 0xffff0000, v168
	v_pk_fma_f32 v[90:91], v[90:91], v[224:225], v[230:231]
	v_lshlrev_b32_e32 v226, 16, v169
	v_and_b32_e32 v227, 0xffff0000, v169
	v_pk_fma_f32 v[92:93], v[92:93], v[226:227], v[230:231]
	v_cvt_pk_bf16_f32 v94, v94, v95
	v_cvt_pk_bf16_f32 v95, v96, v97
	v_cvt_pk_bf16_f32 v96, v90, v91
	v_cvt_pk_bf16_f32 v97, v92, v93
	s_add_u32 s76, s72, 0x8000
	s_addc_u32 s77, s73, 0
	global_store_dwordx4 v232, v[94:97], s[76:77]
	s_add_u32 s4, s70, 0x18000
	s_addc_u32 s5, s71, 0
	global_load_dwordx4 v[166:169], v232, s[4:5] nt
	s_waitcnt vmcnt(12)
	v_lshlrev_b32_e32 v224, 16, v170
	v_and_b32_e32 v225, 0xffff0000, v170
	v_pk_fma_f32 v[86:87], v[86:87], v[224:225], v[230:231]
	v_lshlrev_b32_e32 v226, 16, v171
	v_and_b32_e32 v227, 0xffff0000, v171
	v_pk_fma_f32 v[88:89], v[88:89], v[226:227], v[230:231]
	v_lshlrev_b32_e32 v224, 16, v172
	v_and_b32_e32 v225, 0xffff0000, v172
	v_pk_fma_f32 v[82:83], v[82:83], v[224:225], v[230:231]
	v_lshlrev_b32_e32 v226, 16, v173
	v_and_b32_e32 v227, 0xffff0000, v173
	v_pk_fma_f32 v[84:85], v[84:85], v[226:227], v[230:231]
	v_cvt_pk_bf16_f32 v86, v86, v87
	v_cvt_pk_bf16_f32 v87, v88, v89
	v_cvt_pk_bf16_f32 v88, v82, v83
	v_cvt_pk_bf16_f32 v89, v84, v85
	s_add_u32 s76, s72, 0xa000
	s_addc_u32 s77, s73, 0
	global_store_dwordx4 v232, v[86:89], s[76:77]
	s_add_u32 s4, s70, 0x1a000
	s_addc_u32 s5, s71, 0
	global_load_dwordx4 v[170:173], v232, s[4:5] nt
	s_waitcnt vmcnt(13)
	v_lshlrev_b32_e32 v224, 16, v174
	v_and_b32_e32 v225, 0xffff0000, v174
	v_pk_fma_f32 v[78:79], v[78:79], v[224:225], v[230:231]
	v_lshlrev_b32_e32 v226, 16, v175
	v_and_b32_e32 v227, 0xffff0000, v175
	v_pk_fma_f32 v[80:81], v[80:81], v[226:227], v[230:231]
	v_lshlrev_b32_e32 v224, 16, v176
	v_and_b32_e32 v225, 0xffff0000, v176
	v_pk_fma_f32 v[74:75], v[74:75], v[224:225], v[230:231]
	v_lshlrev_b32_e32 v226, 16, v177
	v_and_b32_e32 v227, 0xffff0000, v177
	v_pk_fma_f32 v[76:77], v[76:77], v[226:227], v[230:231]
	v_cvt_pk_bf16_f32 v78, v78, v79
	v_cvt_pk_bf16_f32 v79, v80, v81
	v_cvt_pk_bf16_f32 v80, v74, v75
	v_cvt_pk_bf16_f32 v81, v76, v77
	s_add_u32 s76, s72, 0xc000
	s_addc_u32 s77, s73, 0
	global_store_dwordx4 v232, v[78:81], s[76:77]
	s_add_u32 s4, s70, 0x1c000
	s_addc_u32 s5, s71, 0
	global_load_dwordx4 v[174:177], v232, s[4:5] nt
	s_waitcnt vmcnt(14)
	v_lshlrev_b32_e32 v224, 16, v178
	v_and_b32_e32 v225, 0xffff0000, v178
	v_pk_fma_f32 v[70:71], v[70:71], v[224:225], v[230:231]
	v_lshlrev_b32_e32 v226, 16, v179
	v_and_b32_e32 v227, 0xffff0000, v179
	v_pk_fma_f32 v[72:73], v[72:73], v[226:227], v[230:231]
	v_lshlrev_b32_e32 v224, 16, v180
	v_and_b32_e32 v225, 0xffff0000, v180
	v_pk_fma_f32 v[66:67], v[66:67], v[224:225], v[230:231]
	v_lshlrev_b32_e32 v226, 16, v181
	v_and_b32_e32 v227, 0xffff0000, v181
	v_pk_fma_f32 v[68:69], v[68:69], v[226:227], v[230:231]
	v_cvt_pk_bf16_f32 v70, v70, v71
	v_cvt_pk_bf16_f32 v71, v72, v73
	v_cvt_pk_bf16_f32 v72, v66, v67
	v_cvt_pk_bf16_f32 v73, v68, v69
	s_add_u32 s76, s72, 0xe000
	s_addc_u32 s77, s73, 0
	global_store_dwordx4 v232, v[70:73], s[76:77]
	s_add_u32 s4, s70, 0x1e000
	s_addc_u32 s5, s71, 0
	global_load_dwordx4 v[178:181], v232, s[4:5] nt
	s_waitcnt vmcnt(14)
	v_lshlrev_b32_e32 v224, 16, v130
	v_and_b32_e32 v225, 0xffff0000, v130
	v_pk_fma_f32 v[62:63], v[62:63], v[224:225], v[230:231]
	v_lshlrev_b32_e32 v226, 16, v131
	v_and_b32_e32 v227, 0xffff0000, v131
	v_pk_fma_f32 v[64:65], v[64:65], v[226:227], v[230:231]
	v_lshlrev_b32_e32 v224, 16, v132
	v_and_b32_e32 v225, 0xffff0000, v132
	v_pk_fma_f32 v[58:59], v[58:59], v[224:225], v[230:231]
	v_lshlrev_b32_e32 v226, 16, v133
	v_and_b32_e32 v227, 0xffff0000, v133
	v_pk_fma_f32 v[60:61], v[60:61], v[226:227], v[230:231]
	v_cvt_pk_bf16_f32 v62, v62, v63
	v_cvt_pk_bf16_f32 v63, v64, v65
	v_cvt_pk_bf16_f32 v64, v58, v59
	v_cvt_pk_bf16_f32 v65, v60, v61
	s_add_u32 s76, s72, 0x10000
	s_addc_u32 s77, s73, 0
	global_store_dwordx4 v232, v[62:65], s[76:77]
	s_waitcnt vmcnt(13)
	v_lshlrev_b32_e32 v224, 16, v134
	v_and_b32_e32 v225, 0xffff0000, v134
	v_pk_fma_f32 v[54:55], v[54:55], v[224:225], v[230:231]
	v_lshlrev_b32_e32 v226, 16, v135
	v_and_b32_e32 v227, 0xffff0000, v135
	v_pk_fma_f32 v[56:57], v[56:57], v[226:227], v[230:231]
	v_lshlrev_b32_e32 v224, 16, v136
	v_and_b32_e32 v225, 0xffff0000, v136
	v_pk_fma_f32 v[50:51], v[50:51], v[224:225], v[230:231]
	v_lshlrev_b32_e32 v226, 16, v137
	v_and_b32_e32 v227, 0xffff0000, v137
	v_pk_fma_f32 v[52:53], v[52:53], v[226:227], v[230:231]
	v_cvt_pk_bf16_f32 v54, v54, v55
	v_cvt_pk_bf16_f32 v55, v56, v57
	v_cvt_pk_bf16_f32 v56, v50, v51
	v_cvt_pk_bf16_f32 v57, v52, v53
	s_add_u32 s76, s72, 0x12000
	s_addc_u32 s77, s73, 0
	global_store_dwordx4 v232, v[54:57], s[76:77]
	s_waitcnt vmcnt(12)
	v_lshlrev_b32_e32 v224, 16, v156
	v_and_b32_e32 v225, 0xffff0000, v156
	v_pk_fma_f32 v[46:47], v[46:47], v[224:225], v[230:231]
	v_lshlrev_b32_e32 v226, 16, v157
	v_and_b32_e32 v227, 0xffff0000, v157
	v_pk_fma_f32 v[48:49], v[48:49], v[226:227], v[230:231]
	v_lshlrev_b32_e32 v224, 16, v158
	v_and_b32_e32 v225, 0xffff0000, v158
	v_pk_fma_f32 v[42:43], v[42:43], v[224:225], v[230:231]
	v_lshlrev_b32_e32 v226, 16, v159
	v_and_b32_e32 v227, 0xffff0000, v159
	v_pk_fma_f32 v[44:45], v[44:45], v[226:227], v[230:231]
	v_cvt_pk_bf16_f32 v46, v46, v47
	v_cvt_pk_bf16_f32 v47, v48, v49
	v_cvt_pk_bf16_f32 v48, v42, v43
	v_cvt_pk_bf16_f32 v49, v44, v45
	s_add_u32 s76, s72, 0x14000
	s_addc_u32 s77, s73, 0
	global_store_dwordx4 v232, v[46:49], s[76:77]
	s_waitcnt vmcnt(11)
	v_lshlrev_b32_e32 v224, 16, v162
	v_and_b32_e32 v225, 0xffff0000, v162
	v_pk_fma_f32 v[38:39], v[38:39], v[224:225], v[230:231]
	v_lshlrev_b32_e32 v226, 16, v163
	v_and_b32_e32 v227, 0xffff0000, v163
	v_pk_fma_f32 v[40:41], v[40:41], v[226:227], v[230:231]
	v_lshlrev_b32_e32 v224, 16, v164
	v_and_b32_e32 v225, 0xffff0000, v164
	v_pk_fma_f32 v[34:35], v[34:35], v[224:225], v[230:231]
	v_lshlrev_b32_e32 v226, 16, v165
	v_and_b32_e32 v227, 0xffff0000, v165
	v_pk_fma_f32 v[36:37], v[36:37], v[226:227], v[230:231]
	v_cvt_pk_bf16_f32 v38, v38, v39
	v_cvt_pk_bf16_f32 v39, v40, v41
	v_cvt_pk_bf16_f32 v40, v34, v35
	v_cvt_pk_bf16_f32 v41, v36, v37
	s_add_u32 s76, s72, 0x16000
	s_addc_u32 s77, s73, 0
	global_store_dwordx4 v232, v[38:41], s[76:77]
	s_waitcnt vmcnt(10)
	v_lshlrev_b32_e32 v224, 16, v166
	v_and_b32_e32 v225, 0xffff0000, v166
	v_pk_fma_f32 v[30:31], v[30:31], v[224:225], v[230:231]
	v_lshlrev_b32_e32 v226, 16, v167
	v_and_b32_e32 v227, 0xffff0000, v167
	v_pk_fma_f32 v[32:33], v[32:33], v[226:227], v[230:231]
	v_lshlrev_b32_e32 v224, 16, v168
	v_and_b32_e32 v225, 0xffff0000, v168
	v_pk_fma_f32 v[26:27], v[26:27], v[224:225], v[230:231]
	v_lshlrev_b32_e32 v226, 16, v169
	v_and_b32_e32 v227, 0xffff0000, v169
	v_pk_fma_f32 v[28:29], v[28:29], v[226:227], v[230:231]
	v_cvt_pk_bf16_f32 v30, v30, v31
	v_cvt_pk_bf16_f32 v31, v32, v33
	v_cvt_pk_bf16_f32 v32, v26, v27
	v_cvt_pk_bf16_f32 v33, v28, v29
	s_add_u32 s76, s72, 0x18000
	s_addc_u32 s77, s73, 0
	global_store_dwordx4 v232, v[30:33], s[76:77]
	s_waitcnt vmcnt(9)
	v_lshlrev_b32_e32 v224, 16, v170
	v_and_b32_e32 v225, 0xffff0000, v170
	v_pk_fma_f32 v[22:23], v[22:23], v[224:225], v[230:231]
	v_lshlrev_b32_e32 v226, 16, v171
	v_and_b32_e32 v227, 0xffff0000, v171
	v_pk_fma_f32 v[24:25], v[24:25], v[226:227], v[230:231]
	v_lshlrev_b32_e32 v224, 16, v172
	v_and_b32_e32 v225, 0xffff0000, v172
	v_pk_fma_f32 v[18:19], v[18:19], v[224:225], v[230:231]
	v_lshlrev_b32_e32 v226, 16, v173
	v_and_b32_e32 v227, 0xffff0000, v173
	v_pk_fma_f32 v[20:21], v[20:21], v[226:227], v[230:231]
	v_cvt_pk_bf16_f32 v22, v22, v23
	v_cvt_pk_bf16_f32 v23, v24, v25
	v_cvt_pk_bf16_f32 v24, v18, v19
	v_cvt_pk_bf16_f32 v25, v20, v21
	s_add_u32 s76, s72, 0x1a000
	s_addc_u32 s77, s73, 0
	global_store_dwordx4 v232, v[22:25], s[76:77]
	s_waitcnt vmcnt(8)
	v_lshlrev_b32_e32 v224, 16, v174
	v_and_b32_e32 v225, 0xffff0000, v174
	v_pk_fma_f32 v[14:15], v[14:15], v[224:225], v[230:231]
	v_lshlrev_b32_e32 v226, 16, v175
	v_and_b32_e32 v227, 0xffff0000, v175
	v_pk_fma_f32 v[16:17], v[16:17], v[226:227], v[230:231]
	v_lshlrev_b32_e32 v224, 16, v176
	v_and_b32_e32 v225, 0xffff0000, v176
	v_pk_fma_f32 v[10:11], v[10:11], v[224:225], v[230:231]
	v_lshlrev_b32_e32 v226, 16, v177
	v_and_b32_e32 v227, 0xffff0000, v177
	v_pk_fma_f32 v[12:13], v[12:13], v[226:227], v[230:231]
	v_cvt_pk_bf16_f32 v14, v14, v15
	v_cvt_pk_bf16_f32 v15, v16, v17
	v_cvt_pk_bf16_f32 v16, v10, v11
	v_cvt_pk_bf16_f32 v17, v12, v13
	s_add_u32 s76, s72, 0x1c000
	s_addc_u32 s77, s73, 0
	global_store_dwordx4 v232, v[14:17], s[76:77]
	s_waitcnt vmcnt(7)
	v_lshlrev_b32_e32 v224, 16, v178
	v_and_b32_e32 v225, 0xffff0000, v178
	v_pk_fma_f32 v[6:7], v[6:7], v[224:225], v[230:231]
	v_lshlrev_b32_e32 v226, 16, v179
	v_and_b32_e32 v227, 0xffff0000, v179
	v_pk_fma_f32 v[8:9], v[8:9], v[226:227], v[230:231]
	v_lshlrev_b32_e32 v224, 16, v180
	v_and_b32_e32 v225, 0xffff0000, v180
	v_pk_fma_f32 v[0:1], v[0:1], v[224:225], v[230:231]
	v_lshlrev_b32_e32 v226, 16, v181
	v_and_b32_e32 v227, 0xffff0000, v181
	v_pk_fma_f32 v[2:3], v[2:3], v[226:227], v[230:231]
	v_cvt_pk_bf16_f32 v6, v6, v7
	v_cvt_pk_bf16_f32 v7, v8, v9
	v_cvt_pk_bf16_f32 v8, v0, v1
	v_cvt_pk_bf16_f32 v9, v2, v3
	s_add_u32 s76, s72, 0x1e000
	s_addc_u32 s77, s73, 0
	global_store_dwordx4 v232, v[6:9], s[76:77]
	s_branch .Lmrg_done
.Lmrg_seg1:
	s_add_u32 s70, s26, 0x4512000
	s_addc_u32 s71, s27, 0
	s_add_u32 s70, s70, s4
	s_addc_u32 s71, s71, 0
	s_add_u32 s4, s70, 0x0
	s_addc_u32 s5, s71, 0
	global_load_dwordx4 v[130:133], v232, s[4:5] nt
	s_add_u32 s4, s72, 0x0
	s_addc_u32 s5, s73, 0
	global_load_dwordx4 v[182:185], v232, s[4:5] nt
	s_add_u32 s4, s70, 0x2000
	s_addc_u32 s5, s71, 0
	global_load_dwordx4 v[134:137], v232, s[4:5] nt
	s_add_u32 s4, s72, 0x2000
	s_addc_u32 s5, s73, 0
	global_load_dwordx4 v[186:189], v232, s[4:5] nt
	s_add_u32 s4, s70, 0x4000
	s_addc_u32 s5, s71, 0
	global_load_dwordx4 v[156:159], v232, s[4:5] nt
	s_add_u32 s4, s72, 0x4000
	s_addc_u32 s5, s73, 0
	global_load_dwordx4 v[190:193], v232, s[4:5] nt
	s_add_u32 s4, s70, 0x6000
	s_addc_u32 s5, s71, 0
	global_load_dwordx4 v[162:165], v232, s[4:5] nt
	s_add_u32 s4, s72, 0x6000
	s_addc_u32 s5, s73, 0
	global_load_dwordx4 v[194:197], v232, s[4:5] nt
	s_add_u32 s4, s70, 0x8000
	s_addc_u32 s5, s71, 0
	global_load_dwordx4 v[166:169], v232, s[4:5] nt
	s_add_u32 s4, s72, 0x8000
	s_addc_u32 s5, s73, 0
	global_load_dwordx4 v[198:201], v232, s[4:5] nt
	s_add_u32 s4, s70, 0xa000
	s_addc_u32 s5, s71, 0
	global_load_dwordx4 v[170:173], v232, s[4:5] nt
	s_add_u32 s4, s72, 0xa000
	s_addc_u32 s5, s73, 0
	global_load_dwordx4 v[202:205], v232, s[4:5] nt
	s_add_u32 s4, s70, 0xc000
	s_addc_u32 s5, s71, 0
	global_load_dwordx4 v[174:177], v232, s[4:5] nt
	s_add_u32 s4, s72, 0xc000
	s_addc_u32 s5, s73, 0
	global_load_dwordx4 v[206:209], v232, s[4:5] nt
	s_add_u32 s4, s70, 0xe000
	s_addc_u32 s5, s71, 0
	global_load_dwordx4 v[178:181], v232, s[4:5] nt
	s_add_u32 s4, s72, 0xe000
	s_addc_u32 s5, s73, 0
	global_load_dwordx4 v[210:213], v232, s[4:5] nt
	s_waitcnt vmcnt(14)
	v_lshlrev_b32_e32 v224, 16, v130
	v_and_b32_e32 v225, 0xffff0000, v130
	v_lshlrev_b32_e32 v228, 16, v182
	v_and_b32_e32 v229, 0xffff0000, v182
	v_pk_fma_f32 v[126:127], v[126:127], v[224:225], v[228:229]
	v_lshlrev_b32_e32 v226, 16, v131
	v_and_b32_e32 v227, 0xffff0000, v131
	v_lshlrev_b32_e32 v230, 16, v183
	v_and_b32_e32 v231, 0xffff0000, v183
	v_pk_fma_f32 v[128:129], v[128:129], v[226:227], v[230:231]
	v_lshlrev_b32_e32 v224, 16, v132
	v_and_b32_e32 v225, 0xffff0000, v132
	v_lshlrev_b32_e32 v228, 16, v184
	v_and_b32_e32 v229, 0xffff0000, v184
	v_pk_fma_f32 v[122:123], v[122:123], v[224:225], v[228:229]
	v_lshlrev_b32_e32 v226, 16, v133
	v_and_b32_e32 v227, 0xffff0000, v133
	v_lshlrev_b32_e32 v230, 16, v185
	v_and_b32_e32 v231, 0xffff0000, v185
	v_pk_fma_f32 v[124:125], v[124:125], v[226:227], v[230:231]
	v_cvt_pk_bf16_f32 v126, v126, v127
	v_cvt_pk_bf16_f32 v127, v128, v129
	v_cvt_pk_bf16_f32 v128, v122, v123
	v_cvt_pk_bf16_f32 v129, v124, v125
	s_add_u32 s76, s72, 0x0
	s_addc_u32 s77, s73, 0
	global_store_dwordx4 v232, v[126:129], s[76:77]
	s_add_u32 s4, s70, 0x10000
	s_addc_u32 s5, s71, 0
	global_load_dwordx4 v[130:133], v232, s[4:5] nt
	s_add_u32 s4, s72, 0x10000
	s_addc_u32 s5, s73, 0
	global_load_dwordx4 v[182:185], v232, s[4:5] nt
	s_waitcnt vmcnt(15)
	v_lshlrev_b32_e32 v224, 16, v134
	v_and_b32_e32 v225, 0xffff0000, v134
	v_lshlrev_b32_e32 v228, 16, v186
	v_and_b32_e32 v229, 0xffff0000, v186
	v_pk_fma_f32 v[118:119], v[118:119], v[224:225], v[228:229]
	v_lshlrev_b32_e32 v226, 16, v135
	v_and_b32_e32 v227, 0xffff0000, v135
	v_lshlrev_b32_e32 v230, 16, v187
	v_and_b32_e32 v231, 0xffff0000, v187
	v_pk_fma_f32 v[120:121], v[120:121], v[226:227], v[230:231]
	v_lshlrev_b32_e32 v224, 16, v136
	v_and_b32_e32 v225, 0xffff0000, v136
	v_lshlrev_b32_e32 v228, 16, v188
	v_and_b32_e32 v229, 0xffff0000, v188
	v_pk_fma_f32 v[114:115], v[114:115], v[224:225], v[228:229]
	v_lshlrev_b32_e32 v226, 16, v137
	v_and_b32_e32 v227, 0xffff0000, v137
	v_lshlrev_b32_e32 v230, 16, v189
	v_and_b32_e32 v231, 0xffff0000, v189
	v_pk_fma_f32 v[116:117], v[116:117], v[226:227], v[230:231]
	v_cvt_pk_bf16_f32 v118, v118, v119
	v_cvt_pk_bf16_f32 v119, v120, v121
	v_cvt_pk_bf16_f32 v120, v114, v115
	v_cvt_pk_bf16_f32 v121, v116, v117
	s_add_u32 s76, s72, 0x2000
	s_addc_u32 s77, s73, 0
	global_store_dwordx4 v232, v[118:121], s[76:77]
	s_add_u32 s4, s70, 0x12000
	s_addc_u32 s5, s71, 0
	global_load_dwordx4 v[134:137], v232, s[4:5] nt
	s_add_u32 s4, s72, 0x12000
	s_addc_u32 s5, s73, 0
	global_load_dwordx4 v[186:189], v232, s[4:5] nt
	s_waitcnt vmcnt(16)
	v_lshlrev_b32_e32 v224, 16, v156
	v_and_b32_e32 v225, 0xffff0000, v156
	v_lshlrev_b32_e32 v228, 16, v190
	v_and_b32_e32 v229, 0xffff0000, v190
	v_pk_fma_f32 v[110:111], v[110:111], v[224:225], v[228:229]
	v_lshlrev_b32_e32 v226, 16, v157
	v_and_b32_e32 v227, 0xffff0000, v157
	v_lshlrev_b32_e32 v230, 16, v191
	v_and_b32_e32 v231, 0xffff0000, v191
	v_pk_fma_f32 v[112:113], v[112:113], v[226:227], v[230:231]
	v_lshlrev_b32_e32 v224, 16, v158
	v_and_b32_e32 v225, 0xffff0000, v158
	v_lshlrev_b32_e32 v228, 16, v192
	v_and_b32_e32 v229, 0xffff0000, v192
	v_pk_fma_f32 v[106:107], v[106:107], v[224:225], v[228:229]
	v_lshlrev_b32_e32 v226, 16, v159
	v_and_b32_e32 v227, 0xffff0000, v159
	v_lshlrev_b32_e32 v230, 16, v193
	v_and_b32_e32 v231, 0xffff0000, v193
	v_pk_fma_f32 v[108:109], v[108:109], v[226:227], v[230:231]
	v_cvt_pk_bf16_f32 v110, v110, v111
	v_cvt_pk_bf16_f32 v111, v112, v113
	v_cvt_pk_bf16_f32 v112, v106, v107
	v_cvt_pk_bf16_f32 v113, v108, v109
	s_add_u32 s76, s72, 0x4000
	s_addc_u32 s77, s73, 0
	global_store_dwordx4 v232, v[110:113], s[76:77]
	s_add_u32 s4, s70, 0x14000
	s_addc_u32 s5, s71, 0
	global_load_dwordx4 v[156:159], v232, s[4:5] nt
	s_add_u32 s4, s72, 0x14000
	s_addc_u32 s5, s73, 0
	global_load_dwordx4 v[190:193], v232, s[4:5] nt
	s_waitcnt vmcnt(17)
	v_lshlrev_b32_e32 v224, 16, v162
	v_and_b32_e32 v225, 0xffff0000, v162
	v_lshlrev_b32_e32 v228, 16, v194
	v_and_b32_e32 v229, 0xffff0000, v194
	v_pk_fma_f32 v[102:103], v[102:103], v[224:225], v[228:229]
	v_lshlrev_b32_e32 v226, 16, v163
	v_and_b32_e32 v227, 0xffff0000, v163
	v_lshlrev_b32_e32 v230, 16, v195
	v_and_b32_e32 v231, 0xffff0000, v195
	v_pk_fma_f32 v[104:105], v[104:105], v[226:227], v[230:231]
	v_lshlrev_b32_e32 v224, 16, v164
	v_and_b32_e32 v225, 0xffff0000, v164
	v_lshlrev_b32_e32 v228, 16, v196
	v_and_b32_e32 v229, 0xffff0000, v196
	v_pk_fma_f32 v[98:99], v[98:99], v[224:225], v[228:229]
	v_lshlrev_b32_e32 v226, 16, v165
	v_and_b32_e32 v227, 0xffff0000, v165
	v_lshlrev_b32_e32 v230, 16, v197
	v_and_b32_e32 v231, 0xffff0000, v197
	v_pk_fma_f32 v[100:101], v[100:101], v[226:227], v[230:231]
	v_cvt_pk_bf16_f32 v102, v102, v103
	v_cvt_pk_bf16_f32 v103, v104, v105
	v_cvt_pk_bf16_f32 v104, v98, v99
	v_cvt_pk_bf16_f32 v105, v100, v101
	s_add_u32 s76, s72, 0x6000
	s_addc_u32 s77, s73, 0
	global_store_dwordx4 v232, v[102:105], s[76:77]
	s_add_u32 s4, s70, 0x16000
	s_addc_u32 s5, s71, 0
	global_load_dwordx4 v[162:165], v232, s[4:5] nt
	s_add_u32 s4, s72, 0x16000
	s_addc_u32 s5, s73, 0
	global_load_dwordx4 v[194:197], v232, s[4:5] nt
	s_waitcnt vmcnt(18)
	v_lshlrev_b32_e32 v224, 16, v166
	v_and_b32_e32 v225, 0xffff0000, v166
	v_lshlrev_b32_e32 v228, 16, v198
	v_and_b32_e32 v229, 0xffff0000, v198
	v_pk_fma_f32 v[94:95], v[94:95], v[224:225], v[228:229]
	v_lshlrev_b32_e32 v226, 16, v167
	v_and_b32_e32 v227, 0xffff0000, v167
	v_lshlrev_b32_e32 v230, 16, v199
	v_and_b32_e32 v231, 0xffff0000, v199
	v_pk_fma_f32 v[96:97], v[96:97], v[226:227], v[230:231]
	v_lshlrev_b32_e32 v224, 16, v168
	v_and_b32_e32 v225, 0xffff0000, v168
	v_lshlrev_b32_e32 v228, 16, v200
	v_and_b32_e32 v229, 0xffff0000, v200
	v_pk_fma_f32 v[90:91], v[90:91], v[224:225], v[228:229]
	v_lshlrev_b32_e32 v226, 16, v169
	v_and_b32_e32 v227, 0xffff0000, v169
	v_lshlrev_b32_e32 v230, 16, v201
	v_and_b32_e32 v231, 0xffff0000, v201
	v_pk_fma_f32 v[92:93], v[92:93], v[226:227], v[230:231]
	v_cvt_pk_bf16_f32 v94, v94, v95
	v_cvt_pk_bf16_f32 v95, v96, v97
	v_cvt_pk_bf16_f32 v96, v90, v91
	v_cvt_pk_bf16_f32 v97, v92, v93
	s_add_u32 s76, s72, 0x8000
	s_addc_u32 s77, s73, 0
	global_store_dwordx4 v232, v[94:97], s[76:77]
	s_add_u32 s4, s70, 0x18000
	s_addc_u32 s5, s71, 0
	global_load_dwordx4 v[166:169], v232, s[4:5] nt
	s_add_u32 s4, s72, 0x18000
	s_addc_u32 s5, s73, 0
	global_load_dwordx4 v[198:201], v232, s[4:5] nt
	s_waitcnt vmcnt(19)
	v_lshlrev_b32_e32 v224, 16, v170
	v_and_b32_e32 v225, 0xffff0000, v170
	v_lshlrev_b32_e32 v228, 16, v202
	v_and_b32_e32 v229, 0xffff0000, v202
	v_pk_fma_f32 v[86:87], v[86:87], v[224:225], v[228:229]
	v_lshlrev_b32_e32 v226, 16, v171
	v_and_b32_e32 v227, 0xffff0000, v171
	v_lshlrev_b32_e32 v230, 16, v203
	v_and_b32_e32 v231, 0xffff0000, v203
	v_pk_fma_f32 v[88:89], v[88:89], v[226:227], v[230:231]
	v_lshlrev_b32_e32 v224, 16, v172
	v_and_b32_e32 v225, 0xffff0000, v172
	v_lshlrev_b32_e32 v228, 16, v204
	v_and_b32_e32 v229, 0xffff0000, v204
	v_pk_fma_f32 v[82:83], v[82:83], v[224:225], v[228:229]
	v_lshlrev_b32_e32 v226, 16, v173
	v_and_b32_e32 v227, 0xffff0000, v173
	v_lshlrev_b32_e32 v230, 16, v205
	v_and_b32_e32 v231, 0xffff0000, v205
	v_pk_fma_f32 v[84:85], v[84:85], v[226:227], v[230:231]
	v_cvt_pk_bf16_f32 v86, v86, v87
	v_cvt_pk_bf16_f32 v87, v88, v89
	v_cvt_pk_bf16_f32 v88, v82, v83
	v_cvt_pk_bf16_f32 v89, v84, v85
	s_add_u32 s76, s72, 0xa000
	s_addc_u32 s77, s73, 0
	global_store_dwordx4 v232, v[86:89], s[76:77]
	s_add_u32 s4, s70, 0x1a000
	s_addc_u32 s5, s71, 0
	global_load_dwordx4 v[170:173], v232, s[4:5] nt
	s_add_u32 s4, s72, 0x1a000
	s_addc_u32 s5, s73, 0
	global_load_dwordx4 v[202:205], v232, s[4:5] nt
	s_waitcnt vmcnt(20)
	v_lshlrev_b32_e32 v224, 16, v174
	v_and_b32_e32 v225, 0xffff0000, v174
	v_lshlrev_b32_e32 v228, 16, v206
	v_and_b32_e32 v229, 0xffff0000, v206
	v_pk_fma_f32 v[78:79], v[78:79], v[224:225], v[228:229]
	v_lshlrev_b32_e32 v226, 16, v175
	v_and_b32_e32 v227, 0xffff0000, v175
	v_lshlrev_b32_e32 v230, 16, v207
	v_and_b32_e32 v231, 0xffff0000, v207
	v_pk_fma_f32 v[80:81], v[80:81], v[226:227], v[230:231]
	v_lshlrev_b32_e32 v224, 16, v176
	v_and_b32_e32 v225, 0xffff0000, v176
	v_lshlrev_b32_e32 v228, 16, v208
	v_and_b32_e32 v229, 0xffff0000, v208
	v_pk_fma_f32 v[74:75], v[74:75], v[224:225], v[228:229]
	v_lshlrev_b32_e32 v226, 16, v177
	v_and_b32_e32 v227, 0xffff0000, v177
	v_lshlrev_b32_e32 v230, 16, v209
	v_and_b32_e32 v231, 0xffff0000, v209
	v_pk_fma_f32 v[76:77], v[76:77], v[226:227], v[230:231]
	v_cvt_pk_bf16_f32 v78, v78, v79
	v_cvt_pk_bf16_f32 v79, v80, v81
	v_cvt_pk_bf16_f32 v80, v74, v75
	v_cvt_pk_bf16_f32 v81, v76, v77
	s_add_u32 s76, s72, 0xc000
	s_addc_u32 s77, s73, 0
	global_store_dwordx4 v232, v[78:81], s[76:77]
	s_add_u32 s4, s70, 0x1c000
	s_addc_u32 s5, s71, 0
	global_load_dwordx4 v[174:177], v232, s[4:5] nt
	s_add_u32 s4, s72, 0x1c000
	s_addc_u32 s5, s73, 0
	global_load_dwordx4 v[206:209], v232, s[4:5] nt
	s_waitcnt vmcnt(21)
	v_lshlrev_b32_e32 v224, 16, v178
	v_and_b32_e32 v225, 0xffff0000, v178
	v_lshlrev_b32_e32 v228, 16, v210
	v_and_b32_e32 v229, 0xffff0000, v210
	v_pk_fma_f32 v[70:71], v[70:71], v[224:225], v[228:229]
	v_lshlrev_b32_e32 v226, 16, v179
	v_and_b32_e32 v227, 0xffff0000, v179
	v_lshlrev_b32_e32 v230, 16, v211
	v_and_b32_e32 v231, 0xffff0000, v211
	v_pk_fma_f32 v[72:73], v[72:73], v[226:227], v[230:231]
	v_lshlrev_b32_e32 v224, 16, v180
	v_and_b32_e32 v225, 0xffff0000, v180
	v_lshlrev_b32_e32 v228, 16, v212
	v_and_b32_e32 v229, 0xffff0000, v212
	v_pk_fma_f32 v[66:67], v[66:67], v[224:225], v[228:229]
	v_lshlrev_b32_e32 v226, 16, v181
	v_and_b32_e32 v227, 0xffff0000, v181
	v_lshlrev_b32_e32 v230, 16, v213
	v_and_b32_e32 v231, 0xffff0000, v213
	v_pk_fma_f32 v[68:69], v[68:69], v[226:227], v[230:231]
	v_cvt_pk_bf16_f32 v70, v70, v71
	v_cvt_pk_bf16_f32 v71, v72, v73
	v_cvt_pk_bf16_f32 v72, v66, v67
	v_cvt_pk_bf16_f32 v73, v68, v69
	s_add_u32 s76, s72, 0xe000
	s_addc_u32 s77, s73, 0
	global_store_dwordx4 v232, v[70:73], s[76:77]
	s_add_u32 s4, s70, 0x1e000
	s_addc_u32 s5, s71, 0
	global_load_dwordx4 v[178:181], v232, s[4:5] nt
	s_add_u32 s4, s72, 0x1e000
	s_addc_u32 s5, s73, 0
	global_load_dwordx4 v[210:213], v232, s[4:5] nt
	s_waitcnt vmcnt(21)
	v_lshlrev_b32_e32 v224, 16, v130
	v_and_b32_e32 v225, 0xffff0000, v130
	v_lshlrev_b32_e32 v228, 16, v182
	v_and_b32_e32 v229, 0xffff0000, v182
	v_pk_fma_f32 v[62:63], v[62:63], v[224:225], v[228:229]
	v_lshlrev_b32_e32 v226, 16, v131
	v_and_b32_e32 v227, 0xffff0000, v131
	v_lshlrev_b32_e32 v230, 16, v183
	v_and_b32_e32 v231, 0xffff0000, v183
	v_pk_fma_f32 v[64:65], v[64:65], v[226:227], v[230:231]
	v_lshlrev_b32_e32 v224, 16, v132
	v_and_b32_e32 v225, 0xffff0000, v132
	v_lshlrev_b32_e32 v228, 16, v184
	v_and_b32_e32 v229, 0xffff0000, v184
	v_pk_fma_f32 v[58:59], v[58:59], v[224:225], v[228:229]
	v_lshlrev_b32_e32 v226, 16, v133
	v_and_b32_e32 v227, 0xffff0000, v133
	v_lshlrev_b32_e32 v230, 16, v185
	v_and_b32_e32 v231, 0xffff0000, v185
	v_pk_fma_f32 v[60:61], v[60:61], v[226:227], v[230:231]
	v_cvt_pk_bf16_f32 v62, v62, v63
	v_cvt_pk_bf16_f32 v63, v64, v65
	v_cvt_pk_bf16_f32 v64, v58, v59
	v_cvt_pk_bf16_f32 v65, v60, v61
	s_add_u32 s76, s72, 0x10000
	s_addc_u32 s77, s73, 0
	global_store_dwordx4 v232, v[62:65], s[76:77]
	s_waitcnt vmcnt(19)
	v_lshlrev_b32_e32 v224, 16, v134
	v_and_b32_e32 v225, 0xffff0000, v134
	v_lshlrev_b32_e32 v228, 16, v186
	v_and_b32_e32 v229, 0xffff0000, v186
	v_pk_fma_f32 v[54:55], v[54:55], v[224:225], v[228:229]
	v_lshlrev_b32_e32 v226, 16, v135
	v_and_b32_e32 v227, 0xffff0000, v135
	v_lshlrev_b32_e32 v230, 16, v187
	v_and_b32_e32 v231, 0xffff0000, v187
	v_pk_fma_f32 v[56:57], v[56:57], v[226:227], v[230:231]
	v_lshlrev_b32_e32 v224, 16, v136
	v_and_b32_e32 v225, 0xffff0000, v136
	v_lshlrev_b32_e32 v228, 16, v188
	v_and_b32_e32 v229, 0xffff0000, v188
	v_pk_fma_f32 v[50:51], v[50:51], v[224:225], v[228:229]
	v_lshlrev_b32_e32 v226, 16, v137
	v_and_b32_e32 v227, 0xffff0000, v137
	v_lshlrev_b32_e32 v230, 16, v189
	v_and_b32_e32 v231, 0xffff0000, v189
	v_pk_fma_f32 v[52:53], v[52:53], v[226:227], v[230:231]
	v_cvt_pk_bf16_f32 v54, v54, v55
	v_cvt_pk_bf16_f32 v55, v56, v57
	v_cvt_pk_bf16_f32 v56, v50, v51
	v_cvt_pk_bf16_f32 v57, v52, v53
	s_add_u32 s76, s72, 0x12000
	s_addc_u32 s77, s73, 0
	global_store_dwordx4 v232, v[54:57], s[76:77]
	s_waitcnt vmcnt(17)
	v_lshlrev_b32_e32 v224, 16, v156
	v_and_b32_e32 v225, 0xffff0000, v156
	v_lshlrev_b32_e32 v228, 16, v190
	v_and_b32_e32 v229, 0xffff0000, v190
	v_pk_fma_f32 v[46:47], v[46:47], v[224:225], v[228:229]
	v_lshlrev_b32_e32 v226, 16, v157
	v_and_b32_e32 v227, 0xffff0000, v157
	v_lshlrev_b32_e32 v230, 16, v191
	v_and_b32_e32 v231, 0xffff0000, v191
	v_pk_fma_f32 v[48:49], v[48:49], v[226:227], v[230:231]
	v_lshlrev_b32_e32 v224, 16, v158
	v_and_b32_e32 v225, 0xffff0000, v158
	v_lshlrev_b32_e32 v228, 16, v192
	v_and_b32_e32 v229, 0xffff0000, v192
	v_pk_fma_f32 v[42:43], v[42:43], v[224:225], v[228:229]
	v_lshlrev_b32_e32 v226, 16, v159
	v_and_b32_e32 v227, 0xffff0000, v159
	v_lshlrev_b32_e32 v230, 16, v193
	v_and_b32_e32 v231, 0xffff0000, v193
	v_pk_fma_f32 v[44:45], v[44:45], v[226:227], v[230:231]
	v_cvt_pk_bf16_f32 v46, v46, v47
	v_cvt_pk_bf16_f32 v47, v48, v49
	v_cvt_pk_bf16_f32 v48, v42, v43
	v_cvt_pk_bf16_f32 v49, v44, v45
	s_add_u32 s76, s72, 0x14000
	s_addc_u32 s77, s73, 0
	global_store_dwordx4 v232, v[46:49], s[76:77]
	s_waitcnt vmcnt(15)
	v_lshlrev_b32_e32 v224, 16, v162
	v_and_b32_e32 v225, 0xffff0000, v162
	v_lshlrev_b32_e32 v228, 16, v194
	v_and_b32_e32 v229, 0xffff0000, v194
	v_pk_fma_f32 v[38:39], v[38:39], v[224:225], v[228:229]
	v_lshlrev_b32_e32 v226, 16, v163
	v_and_b32_e32 v227, 0xffff0000, v163
	v_lshlrev_b32_e32 v230, 16, v195
	v_and_b32_e32 v231, 0xffff0000, v195
	v_pk_fma_f32 v[40:41], v[40:41], v[226:227], v[230:231]
	v_lshlrev_b32_e32 v224, 16, v164
	v_and_b32_e32 v225, 0xffff0000, v164
	v_lshlrev_b32_e32 v228, 16, v196
	v_and_b32_e32 v229, 0xffff0000, v196
	v_pk_fma_f32 v[34:35], v[34:35], v[224:225], v[228:229]
	v_lshlrev_b32_e32 v226, 16, v165
	v_and_b32_e32 v227, 0xffff0000, v165
	v_lshlrev_b32_e32 v230, 16, v197
	v_and_b32_e32 v231, 0xffff0000, v197
	v_pk_fma_f32 v[36:37], v[36:37], v[226:227], v[230:231]
	v_cvt_pk_bf16_f32 v38, v38, v39
	v_cvt_pk_bf16_f32 v39, v40, v41
	v_cvt_pk_bf16_f32 v40, v34, v35
	v_cvt_pk_bf16_f32 v41, v36, v37
	s_add_u32 s76, s72, 0x16000
	s_addc_u32 s77, s73, 0
	global_store_dwordx4 v232, v[38:41], s[76:77]
	s_waitcnt vmcnt(13)
	v_lshlrev_b32_e32 v224, 16, v166
	v_and_b32_e32 v225, 0xffff0000, v166
	v_lshlrev_b32_e32 v228, 16, v198
	v_and_b32_e32 v229, 0xffff0000, v198
	v_pk_fma_f32 v[30:31], v[30:31], v[224:225], v[228:229]
	v_lshlrev_b32_e32 v226, 16, v167
	v_and_b32_e32 v227, 0xffff0000, v167
	v_lshlrev_b32_e32 v230, 16, v199
	v_and_b32_e32 v231, 0xffff0000, v199
	v_pk_fma_f32 v[32:33], v[32:33], v[226:227], v[230:231]
	v_lshlrev_b32_e32 v224, 16, v168
	v_and_b32_e32 v225, 0xffff0000, v168
	v_lshlrev_b32_e32 v228, 16, v200
	v_and_b32_e32 v229, 0xffff0000, v200
	v_pk_fma_f32 v[26:27], v[26:27], v[224:225], v[228:229]
	v_lshlrev_b32_e32 v226, 16, v169
	v_and_b32_e32 v227, 0xffff0000, v169
	v_lshlrev_b32_e32 v230, 16, v201
	v_and_b32_e32 v231, 0xffff0000, v201
	v_pk_fma_f32 v[28:29], v[28:29], v[226:227], v[230:231]
	v_cvt_pk_bf16_f32 v30, v30, v31
	v_cvt_pk_bf16_f32 v31, v32, v33
	v_cvt_pk_bf16_f32 v32, v26, v27
	v_cvt_pk_bf16_f32 v33, v28, v29
	s_add_u32 s76, s72, 0x18000
	s_addc_u32 s77, s73, 0
	global_store_dwordx4 v232, v[30:33], s[76:77]
	s_waitcnt vmcnt(11)
	v_lshlrev_b32_e32 v224, 16, v170
	v_and_b32_e32 v225, 0xffff0000, v170
	v_lshlrev_b32_e32 v228, 16, v202
	v_and_b32_e32 v229, 0xffff0000, v202
	v_pk_fma_f32 v[22:23], v[22:23], v[224:225], v[228:229]
	v_lshlrev_b32_e32 v226, 16, v171
	v_and_b32_e32 v227, 0xffff0000, v171
	v_lshlrev_b32_e32 v230, 16, v203
	v_and_b32_e32 v231, 0xffff0000, v203
	v_pk_fma_f32 v[24:25], v[24:25], v[226:227], v[230:231]
	v_lshlrev_b32_e32 v224, 16, v172
	v_and_b32_e32 v225, 0xffff0000, v172
	v_lshlrev_b32_e32 v228, 16, v204
	v_and_b32_e32 v229, 0xffff0000, v204
	v_pk_fma_f32 v[18:19], v[18:19], v[224:225], v[228:229]
	v_lshlrev_b32_e32 v226, 16, v173
	v_and_b32_e32 v227, 0xffff0000, v173
	v_lshlrev_b32_e32 v230, 16, v205
	v_and_b32_e32 v231, 0xffff0000, v205
	v_pk_fma_f32 v[20:21], v[20:21], v[226:227], v[230:231]
	v_cvt_pk_bf16_f32 v22, v22, v23
	v_cvt_pk_bf16_f32 v23, v24, v25
	v_cvt_pk_bf16_f32 v24, v18, v19
	v_cvt_pk_bf16_f32 v25, v20, v21
	s_add_u32 s76, s72, 0x1a000
	s_addc_u32 s77, s73, 0
	global_store_dwordx4 v232, v[22:25], s[76:77]
	s_waitcnt vmcnt(9)
	v_lshlrev_b32_e32 v224, 16, v174
	v_and_b32_e32 v225, 0xffff0000, v174
	v_lshlrev_b32_e32 v228, 16, v206
	v_and_b32_e32 v229, 0xffff0000, v206
	v_pk_fma_f32 v[14:15], v[14:15], v[224:225], v[228:229]
	v_lshlrev_b32_e32 v226, 16, v175
	v_and_b32_e32 v227, 0xffff0000, v175
	v_lshlrev_b32_e32 v230, 16, v207
	v_and_b32_e32 v231, 0xffff0000, v207
	v_pk_fma_f32 v[16:17], v[16:17], v[226:227], v[230:231]
	v_lshlrev_b32_e32 v224, 16, v176
	v_and_b32_e32 v225, 0xffff0000, v176
	v_lshlrev_b32_e32 v228, 16, v208
	v_and_b32_e32 v229, 0xffff0000, v208
	v_pk_fma_f32 v[10:11], v[10:11], v[224:225], v[228:229]
	v_lshlrev_b32_e32 v226, 16, v177
	v_and_b32_e32 v227, 0xffff0000, v177
	v_lshlrev_b32_e32 v230, 16, v209
	v_and_b32_e32 v231, 0xffff0000, v209
	v_pk_fma_f32 v[12:13], v[12:13], v[226:227], v[230:231]
	v_cvt_pk_bf16_f32 v14, v14, v15
	v_cvt_pk_bf16_f32 v15, v16, v17
	v_cvt_pk_bf16_f32 v16, v10, v11
	v_cvt_pk_bf16_f32 v17, v12, v13
	s_add_u32 s76, s72, 0x1c000
	s_addc_u32 s77, s73, 0
	global_store_dwordx4 v232, v[14:17], s[76:77]
	s_waitcnt vmcnt(7)
	v_lshlrev_b32_e32 v224, 16, v178
	v_and_b32_e32 v225, 0xffff0000, v178
	v_lshlrev_b32_e32 v228, 16, v210
	v_and_b32_e32 v229, 0xffff0000, v210
	v_pk_fma_f32 v[6:7], v[6:7], v[224:225], v[228:229]
	v_lshlrev_b32_e32 v226, 16, v179
	v_and_b32_e32 v227, 0xffff0000, v179
	v_lshlrev_b32_e32 v230, 16, v211
	v_and_b32_e32 v231, 0xffff0000, v211
	v_pk_fma_f32 v[8:9], v[8:9], v[226:227], v[230:231]
	v_lshlrev_b32_e32 v224, 16, v180
	v_and_b32_e32 v225, 0xffff0000, v180
	v_lshlrev_b32_e32 v228, 16, v212
	v_and_b32_e32 v229, 0xffff0000, v212
	v_pk_fma_f32 v[0:1], v[0:1], v[224:225], v[228:229]
	v_lshlrev_b32_e32 v226, 16, v181
	v_and_b32_e32 v227, 0xffff0000, v181
	v_lshlrev_b32_e32 v230, 16, v213
	v_and_b32_e32 v231, 0xffff0000, v213
	v_pk_fma_f32 v[2:3], v[2:3], v[226:227], v[230:231]
	v_cvt_pk_bf16_f32 v6, v6, v7
	v_cvt_pk_bf16_f32 v7, v8, v9
	v_cvt_pk_bf16_f32 v8, v0, v1
	v_cvt_pk_bf16_f32 v9, v2, v3
	s_add_u32 s76, s72, 0x1e000
	s_addc_u32 s77, s73, 0
	global_store_dwordx4 v232, v[6:9], s[76:77]
	s_branch .Lmrg_done
